# speedup vs baseline: 1.1227x; 1.0107x over previous
;     ...
;     const int rbase = brow + wr * (BM / 2) + fr;
;     if constexpr (EPI == EPI_RESID) {
;       const int cv = brow < MLAT ? (brow >> 11) : 8;
;       const float* gate = fa + cv * 9216;
;       float* Xp = (float*)(ws + OFF_X);
; #pragma unroll
;       for (int n = 0; n < 4; ++n) {
;         const int col0 = bcol + wc * 64 + n * 16 + fq * 4;
;         float4 g4 = *(const float4*)(gate + col0);
;         g4.x *= cs; g4.y *= cs; g4.z *= cs; g4.w *= cs;
;         float4 b4 = float4{0.f, 0.f, 0.f, 0.f};
;         if (fb) b4 = *(const float4*)(fb + col0);
; #pragma unroll
;         for (int m = 0; m < MT; ++m) {
;           if (sp == 1) {
;             float4 pv;
;             pv.x = g4.x * acc[m][n][0]; pv.y = g4.y * acc[m][n][1]; pv.z = g4.z * acc[m][n][2]; pv.w = g4.w * acc[m][n][3];
;             *(float4*)((float*)(ws + OFF_PART) + (size_t)(rbase + m * 16 - MLAT) * DM + col0) = pv;
;             continue;
;           }
;           float4* px = (float4*)(Xp + (size_t)(rbase + m * 16) * DM + col0);
;           float4 x = *px;
;           x.x = alpha * x.x + g4.x * (acc[m][n][0] + b4.x);
;           x.y = alpha * x.y + g4.y * (acc[m][n][1] + b4.y);
;           x.z = alpha * x.z + g4.z * (acc[m][n][2] + b4.z);
;           x.w = alpha * x.w + g4.w * (acc[m][n][3] + b4.w);
;           *px = x;
;         }
;       }
.LBB0_235:
	v_mfma_f32_16x16x32_bf16 v[88:91], v[84:87], v[24:27], v[60:63]
	v_mfma_f32_16x16x32_bf16 v[60:63], v[136:139], v[24:27], v[116:119]
	v_mfma_f32_16x16x32_bf16 v[24:27], v[152:155], v[24:27], v[156:159]
	v_mfma_f32_16x16x32_bf16 v[184:187], v[52:55], v[176:179], v[160:163]
	v_mfma_f32_16x16x32_bf16 v[116:119], v[84:87], v[176:179], v[164:167]
	v_mfma_f32_16x16x32_bf16 v[84:87], v[136:139], v[176:179], v[168:171]
	v_mfma_f32_16x16x32_bf16 v[52:55], v[152:155], v[176:179], v[172:175]
	s_lshr_b32 s0, s23, 3
	s_mulk_i32 s0, 0x2400
	s_ashr_i32 s1, s0, 31
	s_lshl_b64 s[0:1], s[0:1], 2
	s_add_u32 s0, s25, s0
	s_addc_u32 s1, s74, s1
	v_lshl_add_u32 v136, s23, 8, v245
	v_lshl_or_b32 v138, s22, 8, v244
	v_ashrrev_i32_e32 v139, 31, v138
	v_lshlrev_b64 v[152:153], 2, v[138:139]
	v_lshl_add_u64 v[154:155], s[0:1], 0, v[152:153]
	v_lshlrev_b32_e32 v137, 12, v136
	v_add_u32_e32 v137, v137, v152
	global_load_dwordx4 v[156:159], v[154:155], off
	global_load_dwordx4 v[160:163], v[154:155], off offset:64
	global_load_dwordx4 v[164:167], v[154:155], off offset:128
	global_load_dwordx4 v[168:171], v[154:155], off offset:192
	s_add_u32 s98, s36, 0x0
	s_addc_u32 s99, s37, 0
	global_load_dwordx4 v[172:175], v137, s[98:99]
	s_add_u32 s98, s36, 0x0
	s_addc_u32 s99, s37, 0
	global_load_dwordx4 v[176:179], v137, s[98:99] offset:64
	s_add_u32 s98, s36, 0x0
	s_addc_u32 s99, s37, 0
	global_load_dwordx4 v[180:183], v137, s[98:99] offset:128
	s_add_u32 s98, s36, 0x0
	s_addc_u32 s99, s37, 0
	global_load_dwordx4 v[188:191], v137, s[98:99] offset:192
	s_add_u32 s98, s36, 0x10000
	s_addc_u32 s99, s37, 0
	global_load_dwordx4 v[192:195], v137, s[98:99]
	s_add_u32 s98, s36, 0x10000
	s_addc_u32 s99, s37, 0
	global_load_dwordx4 v[196:199], v137, s[98:99] offset:64
	s_waitcnt vmcnt(5)
	v_pk_mul_f32 v[156:157], v[156:157], 0.5 op_sel_hi:[1,0]
	v_pk_mul_f32 v[158:159], v[158:159], 0.5 op_sel_hi:[1,0]
	v_pk_mul_f32 v[172:173], v[172:173], s[52:53] op_sel_hi:[1,0]
	v_pk_mul_f32 v[174:175], v[174:175], s[52:53] op_sel_hi:[1,0]
	v_pk_fma_f32 v[148:149], v[148:149], v[156:157], v[172:173]
	v_pk_fma_f32 v[150:151], v[150:151], v[158:159], v[174:175]
	s_add_u32 s100, s36, 0x0
	s_addc_u32 s101, s37, 0
	global_store_dwordx4 v137, v[148:151], s[100:101]
	s_add_u32 s98, s36, 0x10000
	s_addc_u32 s99, s37, 0
	global_load_dwordx4 v[172:175], v137, s[98:99] offset:128
	s_waitcnt vmcnt(6)
	v_pk_mul_f32 v[160:161], v[160:161], 0.5 op_sel_hi:[1,0]
	v_pk_mul_f32 v[162:163], v[162:163], 0.5 op_sel_hi:[1,0]
	v_pk_mul_f32 v[176:177], v[176:177], s[52:53] op_sel_hi:[1,0]
	v_pk_mul_f32 v[178:179], v[178:179], s[52:53] op_sel_hi:[1,0]
	v_pk_fma_f32 v[112:113], v[112:113], v[160:161], v[176:177]
	v_pk_fma_f32 v[114:115], v[114:115], v[162:163], v[178:179]
	s_add_u32 s100, s36, 0x0
	s_addc_u32 s101, s37, 0
	global_store_dwordx4 v137, v[112:115], s[100:101] offset:64
	s_add_u32 s98, s36, 0x10000
	s_addc_u32 s99, s37, 0
	global_load_dwordx4 v[176:179], v137, s[98:99] offset:192
	s_waitcnt vmcnt(7)
	v_pk_mul_f32 v[164:165], v[164:165], 0.5 op_sel_hi:[1,0]
	v_pk_mul_f32 v[166:167], v[166:167], 0.5 op_sel_hi:[1,0]
	v_pk_mul_f32 v[180:181], v[180:181], s[52:53] op_sel_hi:[1,0]
	v_pk_mul_f32 v[182:183], v[182:183], s[52:53] op_sel_hi:[1,0]
	v_pk_fma_f32 v[80:81], v[80:81], v[164:165], v[180:181]
	v_pk_fma_f32 v[82:83], v[82:83], v[166:167], v[182:183]
	s_add_u32 s100, s36, 0x0
	s_addc_u32 s101, s37, 0
	global_store_dwordx4 v137, v[80:83], s[100:101] offset:128
	s_add_u32 s98, s36, 0x20000
	s_addc_u32 s99, s37, 0
	global_load_dwordx4 v[180:183], v137, s[98:99]
	s_waitcnt vmcnt(8)
	v_pk_mul_f32 v[168:169], v[168:169], 0.5 op_sel_hi:[1,0]
	v_pk_mul_f32 v[170:171], v[170:171], 0.5 op_sel_hi:[1,0]
	v_pk_mul_f32 v[188:189], v[188:189], s[52:53] op_sel_hi:[1,0]
	v_pk_mul_f32 v[190:191], v[190:191], s[52:53] op_sel_hi:[1,0]
	v_pk_fma_f32 v[48:49], v[48:49], v[168:169], v[188:189]
	v_pk_fma_f32 v[50:51], v[50:51], v[170:171], v[190:191]
	s_add_u32 s100, s36, 0x0
	s_addc_u32 s101, s37, 0
	global_store_dwordx4 v137, v[48:51], s[100:101] offset:192
	s_add_u32 s98, s36, 0x20000
	s_addc_u32 s99, s37, 0
	global_load_dwordx4 v[188:191], v137, s[98:99] offset:64
	s_waitcnt vmcnt(9)
	v_pk_mul_f32 v[192:193], v[192:193], s[52:53] op_sel_hi:[1,0]
	v_pk_mul_f32 v[194:195], v[194:195], s[52:53] op_sel_hi:[1,0]
	v_pk_fma_f32 v[144:145], v[144:145], v[156:157], v[192:193]
	v_pk_fma_f32 v[146:147], v[146:147], v[158:159], v[194:195]
	s_add_u32 s100, s36, 0x10000
	s_addc_u32 s101, s37, 0
	global_store_dwordx4 v137, v[144:147], s[100:101]
	s_add_u32 s98, s36, 0x20000
	s_addc_u32 s99, s37, 0
	global_load_dwordx4 v[192:195], v137, s[98:99] offset:128
	s_waitcnt vmcnt(10)
	v_pk_mul_f32 v[196:197], v[196:197], s[52:53] op_sel_hi:[1,0]
	v_pk_mul_f32 v[198:199], v[198:199], s[52:53] op_sel_hi:[1,0]
	v_pk_fma_f32 v[108:109], v[108:109], v[160:161], v[196:197]
	v_pk_fma_f32 v[110:111], v[110:111], v[162:163], v[198:199]
	s_add_u32 s100, s36, 0x10000
	s_addc_u32 s101, s37, 0
	global_store_dwordx4 v137, v[108:111], s[100:101] offset:64
	s_add_u32 s98, s36, 0x20000
	s_addc_u32 s99, s37, 0
	global_load_dwordx4 v[196:199], v137, s[98:99] offset:192
	s_waitcnt vmcnt(10)
	v_pk_mul_f32 v[172:173], v[172:173], s[52:53] op_sel_hi:[1,0]
	v_pk_mul_f32 v[174:175], v[174:175], s[52:53] op_sel_hi:[1,0]
	v_pk_fma_f32 v[76:77], v[76:77], v[164:165], v[172:173]
	v_pk_fma_f32 v[78:79], v[78:79], v[166:167], v[174:175]
	s_add_u32 s100, s36, 0x10000
	s_addc_u32 s101, s37, 0
	global_store_dwordx4 v137, v[76:79], s[100:101] offset:128
	s_add_u32 s98, s36, 0x30000
	s_addc_u32 s99, s37, 0
	global_load_dwordx4 v[172:175], v137, s[98:99]
	s_waitcnt vmcnt(10)
;     ...
;     const int rbase = brow + wr * (BM / 2) + fr;
;     if constexpr (EPI == EPI_RESID) {
;       const int cv = brow < MLAT ? (brow >> 11) : 8;
;       const float* gate = fa + cv * 9216;
;       float* Xp = (float*)(ws + OFF_X);
; #pragma unroll
;       for (int n = 0; n < 4; ++n) {
;         const int col0 = bcol + wc * 64 + n * 16 + fq * 4;
;         float4 g4 = *(const float4*)(gate + col0);
;         g4.x *= cs; g4.y *= cs; g4.z *= cs; g4.w *= cs;
;         float4 b4 = float4{0.f, 0.f, 0.f, 0.f};
;         if (fb) b4 = *(const float4*)(fb + col0);
; #pragma unroll
;         for (int m = 0; m < MT; ++m) {
;           if (sp == 1) {
;             float4 pv;
;             pv.x = g4.x * acc[m][n][0]; pv.y = g4.y * acc[m][n][1]; pv.z = g4.z * acc[m][n][2]; pv.w = g4.w * acc[m][n][3];
;             *(float4*)((float*)(ws + OFF_PART) + (size_t)(rbase + m * 16 - MLAT) * DM + col0) = pv;
;             continue;
;           }
;           float4* px = (float4*)(Xp + (size_t)(rbase + m * 16) * DM + col0);
;           float4 x = *px;
;           x.x = alpha * x.x + g4.x * (acc[m][n][0] + b4.x);
;           x.y = alpha * x.y + g4.y * (acc[m][n][1] + b4.y);
;           x.z = alpha * x.z + g4.z * (acc[m][n][2] + b4.z);
;           x.w = alpha * x.w + g4.w * (acc[m][n][3] + b4.w);
;           *px = x;
;         }
;       }
	v_pk_mul_f32 v[176:177], v[176:177], s[52:53] op_sel_hi:[1,0]
	v_pk_mul_f32 v[178:179], v[178:179], s[52:53] op_sel_hi:[1,0]
	v_pk_fma_f32 v[44:45], v[44:45], v[168:169], v[176:177]
	v_pk_fma_f32 v[46:47], v[46:47], v[170:171], v[178:179]
	s_add_u32 s100, s36, 0x10000
	s_addc_u32 s101, s37, 0
	global_store_dwordx4 v137, v[44:47], s[100:101] offset:192
	s_add_u32 s98, s36, 0x30000
	s_addc_u32 s99, s37, 0
	global_load_dwordx4 v[176:179], v137, s[98:99] offset:64
	s_waitcnt vmcnt(10)
	v_pk_mul_f32 v[180:181], v[180:181], s[52:53] op_sel_hi:[1,0]
	v_pk_mul_f32 v[182:183], v[182:183], s[52:53] op_sel_hi:[1,0]
	v_pk_fma_f32 v[140:141], v[140:141], v[156:157], v[180:181]
	v_pk_fma_f32 v[142:143], v[142:143], v[158:159], v[182:183]
	s_add_u32 s100, s36, 0x20000
	s_addc_u32 s101, s37, 0
	global_store_dwordx4 v137, v[140:143], s[100:101]
	s_add_u32 s98, s36, 0x30000
	s_addc_u32 s99, s37, 0
	global_load_dwordx4 v[180:183], v137, s[98:99] offset:128
	s_waitcnt vmcnt(10)
	v_pk_mul_f32 v[188:189], v[188:189], s[52:53] op_sel_hi:[1,0]
	v_pk_mul_f32 v[190:191], v[190:191], s[52:53] op_sel_hi:[1,0]
	v_pk_fma_f32 v[104:105], v[104:105], v[160:161], v[188:189]
	v_pk_fma_f32 v[106:107], v[106:107], v[162:163], v[190:191]
	s_add_u32 s100, s36, 0x20000
	s_addc_u32 s101, s37, 0
	global_store_dwordx4 v137, v[104:107], s[100:101] offset:64
	s_add_u32 s98, s36, 0x30000
	s_addc_u32 s99, s37, 0
	global_load_dwordx4 v[188:191], v137, s[98:99] offset:192
	s_waitcnt vmcnt(10)
	v_pk_mul_f32 v[192:193], v[192:193], s[52:53] op_sel_hi:[1,0]
	v_pk_mul_f32 v[194:195], v[194:195], s[52:53] op_sel_hi:[1,0]
	v_pk_fma_f32 v[72:73], v[72:73], v[164:165], v[192:193]
	v_pk_fma_f32 v[74:75], v[74:75], v[166:167], v[194:195]
	s_add_u32 s100, s36, 0x20000
	s_addc_u32 s101, s37, 0
	global_store_dwordx4 v137, v[72:75], s[100:101] offset:128
	s_add_u32 s98, s36, 0x40000
	s_addc_u32 s99, s37, 0
	global_load_dwordx4 v[192:195], v137, s[98:99]
	s_waitcnt vmcnt(10)
	v_pk_mul_f32 v[196:197], v[196:197], s[52:53] op_sel_hi:[1,0]
	v_pk_mul_f32 v[198:199], v[198:199], s[52:53] op_sel_hi:[1,0]
	v_pk_fma_f32 v[40:41], v[40:41], v[168:169], v[196:197]
	v_pk_fma_f32 v[42:43], v[42:43], v[170:171], v[198:199]
	s_add_u32 s100, s36, 0x20000
	s_addc_u32 s101, s37, 0
	global_store_dwordx4 v137, v[40:43], s[100:101] offset:192
	s_add_u32 s98, s36, 0x40000
	s_addc_u32 s99, s37, 0
	global_load_dwordx4 v[196:199], v137, s[98:99] offset:64
	s_waitcnt vmcnt(10)
	v_pk_mul_f32 v[172:173], v[172:173], s[52:53] op_sel_hi:[1,0]
	v_pk_mul_f32 v[174:175], v[174:175], s[52:53] op_sel_hi:[1,0]
	v_pk_fma_f32 v[132:133], v[132:133], v[156:157], v[172:173]
	v_pk_fma_f32 v[134:135], v[134:135], v[158:159], v[174:175]
	s_add_u32 s100, s36, 0x30000
	s_addc_u32 s101, s37, 0
	global_store_dwordx4 v137, v[132:135], s[100:101]
	s_add_u32 s98, s36, 0x40000
	s_addc_u32 s99, s37, 0
	global_load_dwordx4 v[172:175], v137, s[98:99] offset:128
	s_waitcnt vmcnt(10)
	v_pk_mul_f32 v[176:177], v[176:177], s[52:53] op_sel_hi:[1,0]
	v_pk_mul_f32 v[178:179], v[178:179], s[52:53] op_sel_hi:[1,0]
	v_pk_fma_f32 v[100:101], v[100:101], v[160:161], v[176:177]
	v_pk_fma_f32 v[102:103], v[102:103], v[162:163], v[178:179]
	s_add_u32 s100, s36, 0x30000
	s_addc_u32 s101, s37, 0
	global_store_dwordx4 v137, v[100:103], s[100:101] offset:64
	s_add_u32 s98, s36, 0x40000
	s_addc_u32 s99, s37, 0
	global_load_dwordx4 v[176:179], v137, s[98:99] offset:192
	s_waitcnt vmcnt(10)
	v_pk_mul_f32 v[180:181], v[180:181], s[52:53] op_sel_hi:[1,0]
	v_pk_mul_f32 v[182:183], v[182:183], s[52:53] op_sel_hi:[1,0]
	v_pk_fma_f32 v[68:69], v[68:69], v[164:165], v[180:181]
	v_pk_fma_f32 v[70:71], v[70:71], v[166:167], v[182:183]
	s_add_u32 s100, s36, 0x30000
	s_addc_u32 s101, s37, 0
	global_store_dwordx4 v137, v[68:71], s[100:101] offset:128
	s_add_u32 s98, s36, 0x50000
	s_addc_u32 s99, s37, 0
	global_load_dwordx4 v[180:183], v137, s[98:99]
	s_waitcnt vmcnt(10)
	v_pk_mul_f32 v[188:189], v[188:189], s[52:53] op_sel_hi:[1,0]
	v_pk_mul_f32 v[190:191], v[190:191], s[52:53] op_sel_hi:[1,0]
	v_pk_fma_f32 v[36:37], v[36:37], v[168:169], v[188:189]
	v_pk_fma_f32 v[38:39], v[38:39], v[170:171], v[190:191]
	s_add_u32 s100, s36, 0x30000
	s_addc_u32 s101, s37, 0
	global_store_dwordx4 v137, v[36:39], s[100:101] offset:192
	s_add_u32 s98, s36, 0x50000
	s_addc_u32 s99, s37, 0
	global_load_dwordx4 v[188:191], v137, s[98:99] offset:64
	s_waitcnt vmcnt(10)
	v_pk_mul_f32 v[192:193], v[192:193], s[52:53] op_sel_hi:[1,0]
	v_pk_mul_f32 v[194:195], v[194:195], s[52:53] op_sel_hi:[1,0]
	v_pk_fma_f32 v[128:129], v[128:129], v[156:157], v[192:193]
	v_pk_fma_f32 v[130:131], v[130:131], v[158:159], v[194:195]
	s_add_u32 s100, s36, 0x40000
	s_addc_u32 s101, s37, 0
	global_store_dwordx4 v137, v[128:131], s[100:101]
	s_add_u32 s98, s36, 0x50000
	s_addc_u32 s99, s37, 0
	global_load_dwordx4 v[192:195], v137, s[98:99] offset:128
	s_waitcnt vmcnt(10)
	v_pk_mul_f32 v[196:197], v[196:197], s[52:53] op_sel_hi:[1,0]
	v_pk_mul_f32 v[198:199], v[198:199], s[52:53] op_sel_hi:[1,0]
	v_pk_fma_f32 v[96:97], v[96:97], v[160:161], v[196:197]
	v_pk_fma_f32 v[98:99], v[98:99], v[162:163], v[198:199]
	s_add_u32 s100, s36, 0x40000
	s_addc_u32 s101, s37, 0
	global_store_dwordx4 v137, v[96:99], s[100:101] offset:64
	s_add_u32 s98, s36, 0x50000
	s_addc_u32 s99, s37, 0
	global_load_dwordx4 v[196:199], v137, s[98:99] offset:192
	s_waitcnt vmcnt(10)
	v_pk_mul_f32 v[172:173], v[172:173], s[52:53] op_sel_hi:[1,0]
	v_pk_mul_f32 v[174:175], v[174:175], s[52:53] op_sel_hi:[1,0]
	v_pk_fma_f32 v[64:65], v[64:65], v[164:165], v[172:173]
	v_pk_fma_f32 v[66:67], v[66:67], v[166:167], v[174:175]
	s_add_u32 s100, s36, 0x40000
	s_addc_u32 s101, s37, 0
	global_store_dwordx4 v137, v[64:67], s[100:101] offset:128
	s_add_u32 s98, s36, 0x60000
	s_addc_u32 s99, s37, 0
	global_load_dwordx4 v[172:175], v137, s[98:99]
	s_waitcnt vmcnt(10)
;     ...
;     const int rbase = brow + wr * (BM / 2) + fr;
;     if constexpr (EPI == EPI_RESID) {
;       const int cv = brow < MLAT ? (brow >> 11) : 8;
;       const float* gate = fa + cv * 9216;
;       float* Xp = (float*)(ws + OFF_X);
; #pragma unroll
;       for (int n = 0; n < 4; ++n) {
;         const int col0 = bcol + wc * 64 + n * 16 + fq * 4;
;         float4 g4 = *(const float4*)(gate + col0);
;         g4.x *= cs; g4.y *= cs; g4.z *= cs; g4.w *= cs;
;         float4 b4 = float4{0.f, 0.f, 0.f, 0.f};
;         if (fb) b4 = *(const float4*)(fb + col0);
; #pragma unroll
;         for (int m = 0; m < MT; ++m) {
;           if (sp == 1) {
;             float4 pv;
;             pv.x = g4.x * acc[m][n][0]; pv.y = g4.y * acc[m][n][1]; pv.z = g4.z * acc[m][n][2]; pv.w = g4.w * acc[m][n][3];
;             *(float4*)((float*)(ws + OFF_PART) + (size_t)(rbase + m * 16 - MLAT) * DM + col0) = pv;
;             continue;
;           }
;           float4* px = (float4*)(Xp + (size_t)(rbase + m * 16) * DM + col0);
;           float4 x = *px;
;           x.x = alpha * x.x + g4.x * (acc[m][n][0] + b4.x);
;           x.y = alpha * x.y + g4.y * (acc[m][n][1] + b4.y);
;           x.z = alpha * x.z + g4.z * (acc[m][n][2] + b4.z);
;           x.w = alpha * x.w + g4.w * (acc[m][n][3] + b4.w);
;           *px = x;
;         }
;       }
	v_pk_mul_f32 v[176:177], v[176:177], s[52:53] op_sel_hi:[1,0]
	v_pk_mul_f32 v[178:179], v[178:179], s[52:53] op_sel_hi:[1,0]
	v_pk_fma_f32 v[32:33], v[32:33], v[168:169], v[176:177]
	v_pk_fma_f32 v[34:35], v[34:35], v[170:171], v[178:179]
	s_add_u32 s100, s36, 0x40000
	s_addc_u32 s101, s37, 0
	global_store_dwordx4 v137, v[32:35], s[100:101] offset:192
	s_add_u32 s98, s36, 0x60000
	s_addc_u32 s99, s37, 0
	global_load_dwordx4 v[176:179], v137, s[98:99] offset:64
	s_waitcnt vmcnt(10)
	v_pk_mul_f32 v[180:181], v[180:181], s[52:53] op_sel_hi:[1,0]
	v_pk_mul_f32 v[182:183], v[182:183], s[52:53] op_sel_hi:[1,0]
	v_pk_fma_f32 v[124:125], v[124:125], v[156:157], v[180:181]
	v_pk_fma_f32 v[126:127], v[126:127], v[158:159], v[182:183]
	s_add_u32 s100, s36, 0x50000
	s_addc_u32 s101, s37, 0
	global_store_dwordx4 v137, v[124:127], s[100:101]
	s_add_u32 s98, s36, 0x60000
	s_addc_u32 s99, s37, 0
	global_load_dwordx4 v[180:183], v137, s[98:99] offset:128
	s_waitcnt vmcnt(10)
	v_pk_mul_f32 v[188:189], v[188:189], s[52:53] op_sel_hi:[1,0]
	v_pk_mul_f32 v[190:191], v[190:191], s[52:53] op_sel_hi:[1,0]
	v_pk_fma_f32 v[92:93], v[92:93], v[160:161], v[188:189]
	v_pk_fma_f32 v[94:95], v[94:95], v[162:163], v[190:191]
	s_add_u32 s100, s36, 0x50000
	s_addc_u32 s101, s37, 0
	global_store_dwordx4 v137, v[92:95], s[100:101] offset:64
	s_add_u32 s98, s36, 0x60000
	s_addc_u32 s99, s37, 0
	global_load_dwordx4 v[188:191], v137, s[98:99] offset:192
	s_waitcnt vmcnt(10)
	v_pk_mul_f32 v[192:193], v[192:193], s[52:53] op_sel_hi:[1,0]
	v_pk_mul_f32 v[194:195], v[194:195], s[52:53] op_sel_hi:[1,0]
	v_pk_fma_f32 v[56:57], v[56:57], v[164:165], v[192:193]
	v_pk_fma_f32 v[58:59], v[58:59], v[166:167], v[194:195]
	s_add_u32 s100, s36, 0x50000
	s_addc_u32 s101, s37, 0
	global_store_dwordx4 v137, v[56:59], s[100:101] offset:128
	s_add_u32 s98, s36, 0x70000
	s_addc_u32 s99, s37, 0
	global_load_dwordx4 v[192:195], v137, s[98:99]
	s_waitcnt vmcnt(10)
	v_pk_mul_f32 v[196:197], v[196:197], s[52:53] op_sel_hi:[1,0]
	v_pk_mul_f32 v[198:199], v[198:199], s[52:53] op_sel_hi:[1,0]
	v_pk_fma_f32 v[28:29], v[28:29], v[168:169], v[196:197]
	v_pk_fma_f32 v[30:31], v[30:31], v[170:171], v[198:199]
	s_add_u32 s100, s36, 0x50000
	s_addc_u32 s101, s37, 0
	global_store_dwordx4 v137, v[28:31], s[100:101] offset:192
	s_add_u32 s98, s36, 0x70000
	s_addc_u32 s99, s37, 0
	global_load_dwordx4 v[196:199], v137, s[98:99] offset:64
	s_waitcnt vmcnt(10)
	v_pk_mul_f32 v[172:173], v[172:173], s[52:53] op_sel_hi:[1,0]
	v_pk_mul_f32 v[174:175], v[174:175], s[52:53] op_sel_hi:[1,0]
	v_pk_fma_f32 v[120:121], v[120:121], v[156:157], v[172:173]
	v_pk_fma_f32 v[122:123], v[122:123], v[158:159], v[174:175]
	s_add_u32 s100, s36, 0x60000
	s_addc_u32 s101, s37, 0
	global_store_dwordx4 v137, v[120:123], s[100:101]
	s_add_u32 s98, s36, 0x70000
	s_addc_u32 s99, s37, 0
	global_load_dwordx4 v[172:175], v137, s[98:99] offset:128
	s_waitcnt vmcnt(10)
	v_pk_mul_f32 v[176:177], v[176:177], s[52:53] op_sel_hi:[1,0]
	v_pk_mul_f32 v[178:179], v[178:179], s[52:53] op_sel_hi:[1,0]
	v_pk_fma_f32 v[88:89], v[88:89], v[160:161], v[176:177]
	v_pk_fma_f32 v[90:91], v[90:91], v[162:163], v[178:179]
	s_add_u32 s100, s36, 0x60000
	s_addc_u32 s101, s37, 0
	global_store_dwordx4 v137, v[88:91], s[100:101] offset:64
	s_add_u32 s98, s36, 0x70000
	s_addc_u32 s99, s37, 0
	global_load_dwordx4 v[176:179], v137, s[98:99] offset:192
	s_waitcnt vmcnt(10)
	v_pk_mul_f32 v[180:181], v[180:181], s[52:53] op_sel_hi:[1,0]
	v_pk_mul_f32 v[182:183], v[182:183], s[52:53] op_sel_hi:[1,0]
	v_pk_fma_f32 v[60:61], v[60:61], v[164:165], v[180:181]
	v_pk_fma_f32 v[62:63], v[62:63], v[166:167], v[182:183]
	s_add_u32 s100, s36, 0x60000
	s_addc_u32 s101, s37, 0
	global_store_dwordx4 v137, v[60:63], s[100:101] offset:128
	s_waitcnt vmcnt(9)
	v_pk_mul_f32 v[188:189], v[188:189], s[52:53] op_sel_hi:[1,0]
	v_pk_mul_f32 v[190:191], v[190:191], s[52:53] op_sel_hi:[1,0]
	v_pk_fma_f32 v[24:25], v[24:25], v[168:169], v[188:189]
	v_pk_fma_f32 v[26:27], v[26:27], v[170:171], v[190:191]
	s_add_u32 s100, s36, 0x60000
	s_addc_u32 s101, s37, 0
	global_store_dwordx4 v137, v[24:27], s[100:101] offset:192
	s_waitcnt vmcnt(8)
	v_pk_mul_f32 v[192:193], v[192:193], s[52:53] op_sel_hi:[1,0]
	v_pk_mul_f32 v[194:195], v[194:195], s[52:53] op_sel_hi:[1,0]
	v_pk_fma_f32 v[184:185], v[184:185], v[156:157], v[192:193]
	v_pk_fma_f32 v[186:187], v[186:187], v[158:159], v[194:195]
	s_add_u32 s100, s36, 0x70000
	s_addc_u32 s101, s37, 0
	global_store_dwordx4 v137, v[184:187], s[100:101]
	s_waitcnt vmcnt(7)
	v_pk_mul_f32 v[196:197], v[196:197], s[52:53] op_sel_hi:[1,0]
	v_pk_mul_f32 v[198:199], v[198:199], s[52:53] op_sel_hi:[1,0]
	v_pk_fma_f32 v[116:117], v[116:117], v[160:161], v[196:197]
	v_pk_fma_f32 v[118:119], v[118:119], v[162:163], v[198:199]
	s_add_u32 s100, s36, 0x70000
	s_addc_u32 s101, s37, 0
	global_store_dwordx4 v137, v[116:119], s[100:101] offset:64
	s_waitcnt vmcnt(6)
	v_pk_mul_f32 v[172:173], v[172:173], s[52:53] op_sel_hi:[1,0]
	v_pk_mul_f32 v[174:175], v[174:175], s[52:53] op_sel_hi:[1,0]
	v_pk_fma_f32 v[84:85], v[84:85], v[164:165], v[172:173]
	v_pk_fma_f32 v[86:87], v[86:87], v[166:167], v[174:175]
	s_add_u32 s100, s36, 0x70000
	s_addc_u32 s101, s37, 0
	global_store_dwordx4 v137, v[84:87], s[100:101] offset:128
	s_waitcnt vmcnt(5)
	v_pk_mul_f32 v[176:177], v[176:177], s[52:53] op_sel_hi:[1,0]
	v_pk_mul_f32 v[178:179], v[178:179], s[52:53] op_sel_hi:[1,0]
	v_pk_fma_f32 v[52:53], v[52:53], v[168:169], v[176:177]
	v_pk_fma_f32 v[54:55], v[54:55], v[170:171], v[178:179]
	s_add_u32 s100, s36, 0x70000
	s_addc_u32 s101, s37, 0
	global_store_dwordx4 v137, v[52:55], s[100:101] offset:192
	s_and_b64 vcc, exec, s[14:15]
	s_mov_b32 s23, s21
	s_mov_b32 s22, s20
	s_mov_b64 s[18:19], s[6:7]
	s_mov_b64 s[0:1], s[12:13]
	s_cbranch_vccnz .LBB0_244
